# last grid barrier: 4-party row-panel counter releases the out-projection K loop; grid-wide wait deferred to before the fused epilogue's first write
# baseline (speedup 1.0000x reference)
; __device__ __forceinline__ void xcd_barrier(const XcdBarrier& b) {
;     asm volatile("s_waitcnt vmcnt(0)" ::: "memory");
;     __syncthreads();
;     if (threadIdx.x == 0) {
;         unsigned* bar = b.bar;
;         __builtin_amdgcn_s_waitcnt(0);
;         unsigned nloc = b.st[0], nx = b.st[1];
;         if (nloc == 0u) { xcd_barrier_complete(bar, b.x, nloc, nx); b.st[0] = nloc; b.st[1] = nx; }
.LBB0_780:
	s_mov_b32 s98, 0
	s_cmp_gt_i32 s91, 8
	s_cselect_b64 s[2:3], -1, 0
	s_and_b64 s[0:1], s[0:1], s[2:3]
	s_andn2_b64 vcc, exec, s[0:1]
	s_cbranch_vccnz .LBB0_830
	s_cmp_eq_u32 s82, 0x100
	s_cselect_b32 s98, 1, 0
	s_waitcnt vmcnt(0)
	s_waitcnt vmcnt(0) lgkmcnt(0)
	s_barrier
	s_mov_b64 s[0:1], exec
	v_readlane_b32 s4, v254, 1
	v_readlane_b32 s5, v254, 2
	s_and_b64 s[4:5], s[0:1], s[4:5]
	s_mov_b64 exec, s[4:5]
	s_cbranch_execz .LBB0_829
	v_readlane_b32 s4, v254, 22
	s_waitcnt vmcnt(0) expcnt(0) lgkmcnt(0)
	s_nop 0
	v_mov_b32_e32 v0, s4
	ds_read_b32 v2, v0
	ds_read_b32 v0, v0 offset:4
	s_waitcnt lgkmcnt(1)
	v_cmp_ne_u32_e32 vcc, 0, v2
	s_cbranch_vccnz .LBB0_797
	v_readlane_b32 s4, v254, 0
	s_mul_i32 s33, s83, s4
	s_add_u32 s4, s88, 0xffc0200
	s_addc_u32 s5, s89, 0
	s_add_u32 s6, s88, 0xffc0400
	s_addc_u32 s7, s89, 0
	s_add_u32 s8, s88, 0xffc0500
	s_addc_u32 s9, s89, 0
	s_add_u32 s10, s88, 0xffc0600
	s_addc_u32 s11, s89, 0
	s_add_u32 s12, s88, 0xffc0700
	s_addc_u32 s13, s89, 0
	s_add_u32 s14, s88, 0xffc0800
	s_addc_u32 s15, s89, 0
	s_add_u32 s16, s88, 0xffc0900
	s_addc_u32 s17, s89, 0
	s_add_u32 s18, s88, 0xffc0a00
	s_addc_u32 s19, s89, 0
	s_add_u32 s20, s88, 0xffc0b00
	s_addc_u32 s21, s89, 0
	s_add_u32 s22, s88, 0xffc0c00
	s_addc_u32 s23, s89, 0
	s_add_u32 s24, s88, 0xffc0d00
	s_addc_u32 s25, s89, 0
	s_add_u32 s26, s88, 0xffc0e00
	s_addc_u32 s27, s89, 0
	s_add_u32 s28, s88, 0xffc0f00
	s_addc_u32 s29, s89, 0
	s_add_u32 s30, s88, 0xffc1000
	s_addc_u32 s31, s89, 0
	s_add_u32 s34, s88, 0xffc1100
	s_addc_u32 s35, s89, 0
	s_add_u32 s36, s88, 0xffc1200
	s_addc_u32 s37, s89, 0
	s_add_u32 s38, s88, 0xffc1300
	s_mul_i32 s33, s33, s82
	s_addc_u32 s39, s89, 0
	s_mov_b32 s46, 1
	v_mov_b32_e32 v16, 0
	s_branch .LBB0_785

;     __device__ __forceinline__ void fused(f32x4 (&acc)[2][2][4][2], const pg8::Unit& u, int wr, int wc, int fr, int fq, LAS unsigned char* lds, int wid, int lane) const {
;     ...
;         if (tid == 0) {
;             __hip_atomic_fetch_add(cnt + u.pm, 1u, __ATOMIC_RELAXED, __HIP_MEMORY_SCOPE_AGENT);
;             for (unsigned sp = 0; sp < (1u << 22); ++sp) { if (__hip_atomic_load(cnt + u.pm, __ATOMIC_RELAXED, __HIP_MEMORY_SCOPE_AGENT) >= 4u) break; __builtin_amdgcn_s_sleep(1); }
;             __builtin_amdgcn_fence(__ATOMIC_ACQUIRE, "agent");
;             asm volatile("s_waitcnt vmcnt(0)" ::: "memory");
;         }
; __global__ void __launch_bounds__(512, 2) mega_fwd(Params p) {
;     ...
;     const bool fuse_out = (G == 256);
;     if (IN(8)) {
;         pg8::Gemm g{(const bf16_t*)(ws + WS_R1 + R1_MG), (const bf16_t*)(ws + WS_WOUT), T_TOK, 1024, 1024}; pg8::StaticOrder S; S.init(T_TOK, 1024, G, bid);
;         if (fuse_out) { EpiRmsRes E{p.x, p.post_w, p.out, (float*)(ws + WS_R2), (unsigned*)(ws + WS_BAR) + 3600}; pg8::gemm_phase<EpiRmsRes, true>(lds, g, S, E); }
.LBB0_830:
	s_cmp_lt_i32 s90, 9
	s_cselect_b64 s[0:1], -1, 0
	s_cmpk_lg_i32 s82, 0x100
	s_cselect_b64 s[6:7], -1, 0
	s_and_b64 s[0:1], s[0:1], s[2:3]
	s_andn2_b64 vcc, exec, s[0:1]
	s_cbranch_vccnz .LBB0_912
	s_cmp_eq_u32 s98, 1
	s_cbranch_scc0 .Ll7_done
	v_readfirstlane_b32 s96, v212
	s_nop 3
	s_cmp_lg_u32 s96, 0
	s_cbranch_scc1 .Ll7_bar
	s_and_b32 s96, s84, 7
	s_lshl_b32 s96, s96, 5
	s_lshr_b32 s97, s84, 3
	s_add_i32 s96, s96, s97
	s_lshr_b32 s97, s96, 4
	s_lshl_b32 s97, s97, 2
	s_and_b32 s96, s96, 3
	s_add_i32 s96, s96, s97
	s_lshl_b32 s96, s96, 2
	v_mov_b32_e32 v250, 0xffc39d0
	v_add_u32_e32 v250, s96, v250
	v_mov_b32_e32 v251, 1
	v_mbcnt_lo_u32_b32 v252, -1, 0
	v_mbcnt_hi_u32_b32 v252, -1, v252
	v_cmp_eq_u32_e32 vcc, 0, v252
	s_and_saveexec_b64 s[96:97], vcc
	global_atomic_add v250, v251, s[88:89]
	s_or_b64 exec, exec, s[96:97]
	s_mov_b32 s96, 0
.Ll7_spin:
	global_load_dword v252, v250, s[88:89] sc1
	s_waitcnt vmcnt(0)
	s_nop 1
	v_readfirstlane_b32 s97, v252
	s_nop 3
	s_cmp_ge_u32 s97, 4
	s_cbranch_scc1 .Ll7_acq
	s_sleep 1
	s_add_i32 s96, s96, 1
	s_cmp_lt_u32 s96, 0x40000
	s_cbranch_scc1 .Ll7_spin

;     __device__ bool next(int i, Unit& u) const {
;         const long L = (long)i * G + c; if (L >= nwg) return false;
;         int wgid = (int)L; { const int q = nwg / NXCD, r = nwg % NXCD, xcd = wgid % NXCD, off = wgid / NXCD; wgid = (xcd < r ? xcd * (q + 1) : r * (q + 1) + (xcd - r) * q) + off; }
;         const int nig = WGM * nN, gid = wgid / nig, fm = gid * WGM, gsz = (nM - fm) < WGM ? (nM - fm) : WGM;
;         u.pm = fm + ((wgid % nig) % gsz); u.pn = (wgid % nig) / gsz; return true;
; __global__ void __launch_bounds__(512, 2) mega_fwd(Params p) {
;     ...
;         pg8::Gemm g{(const bf16_t*)(ws + WS_R1 + R1_MG), (const bf16_t*)(ws + WS_WOUT), T_TOK, 1024, 1024}; pg8::StaticOrder S; S.init(T_TOK, 1024, G, bid);
;         if (fuse_out) { EpiRmsRes E{p.x, p.post_w, p.out, (float*)(ws + WS_R2), (unsigned*)(ws + WS_BAR) + 3600}; pg8::gemm_phase<EpiRmsRes, true>(lds, g, S, E); }
.Ll7_done:
	s_add_u32 s33, s88, 0x5d80000
	s_addc_u32 s36, s89, 0
	s_add_u32 s37, s88, 0x1b00000
	s_addc_u32 s38, s89, 0
	s_mov_b64 s[2:3], -1
	s_and_b64 vcc, exec, s[6:7]
	s_cbranch_vccz .LBB0_853
	s_cmpk_gt_i32 s84, 0xff
	v_readfirstlane_b32 s39, v212
	s_cbranch_scc1 .LBB0_852
	s_ashr_i32 s40, s84, 31
	s_lshr_b32 s2, s40, 29
	s_add_i32 s8, s84, s2
	s_and_b32 s2, s8, -8
	s_sub_i32 s5, s84, s2
	s_cmp_gt_i32 s5, -1
	s_cbranch_scc0 .LBB0_835
	s_lshl_b32 s4, s5, 5
	s_ashr_i32 s2, s8, 3
	s_cbranch_execz .LBB0_836
	s_branch .LBB0_837

; #define PG8_STAGE(bufoff, gbase, voff) do { _Pragma("unroll") for (int _i = 0; _i < 2; ++_i) \
;         __builtin_amdgcn_global_load_lds((const unsigned*)((const char*)(gbase) + (voff)[_i]), (LAS unsigned*)(lds + (bufoff) + ldsw + _i * 8192), 16, 0, 0); } while (0)
; #define PG8_LDA(dst, b, h) do { _Pragma("unroll") for (int m = 0; m < 4; ++m) _Pragma("unroll") for (int k = 0; k < 2; ++k) dst[m][k] = *(const LAS bf16x8*)(lds + PG8_SA(b, h) + aoff + m * 2048 + k * 1024); } while (0)
; #define PG8_LDB(dst, b, h) do { _Pragma("unroll") for (int n = 0; n < 2; ++n) _Pragma("unroll") for (int k = 0; k < 2; ++k) dst[n][k] = *(const LAS bf16x8*)(lds + PG8_SB(b, h) + boff + n * 2048 + k * 1024); } while (0)
; #define PG8_MMA(ai, bj, At, Bt) do { __builtin_amdgcn_s_setprio(1); _Pragma("unroll") for (int m = 0; m < 4; ++m) _Pragma("unroll") for (int n = 0; n < 2; ++n) _Pragma("unroll") for (int k = 0; k < 2; ++k) \
;         acc[ai][bj][m][n] = __builtin_amdgcn_mfma_f32_16x16x32_bf16(Bt[n][k], At[m][k], acc[ai][bj][m][n], 0, 0, 0); __builtin_amdgcn_s_setprio(0); } while (0)
; #define PG8_WAIT_L(n) asm volatile("s_waitcnt lgkmcnt(" #n ")" ::: "memory")
; template <class Epi, bool AFTER = false>
; __device__ __forceinline__ void gemm_phase(LAS unsigned char* lds, const Gemm g, const StaticOrder& S, const Epi& E) {
;     ...
;         const bool has_next = S.next(ui + 1, nxt);
;         const char* nA = has_next ? (const char*)g.A + (size_t)nxt.pm * tstep : cA; const char* nB = has_next ? (const char*)g.Bt + (size_t)nxt.pn * tstep : cB;
;         for (int t = 0; t < nt; t += 2) {
;             const bool last = (t == nt - 2);
;             const char* a1 = cA + (size_t)(t + 1) * kstep;
;             const char* a2 = last ? nA : cA + (size_t)(t + 2) * kstep; const char* b2 = last ? nB : cB + (size_t)(t + 2) * kstep;
;             const char* a3 = a2 + kstep; const char* b3 = b2 + kstep;
;             PG8_LDB(B0, 0, 0); PG8_SCHED; PG8_LDA(At, 0, 0); PG8_STAGE(PG8_SA(1, 1), a1 + hstep, voffA);
;             PG8_WAIT_L(8); PG8_BAR; PG8_WAIT_L(0); PG8_MMA(0, 0, At, B0); PG8_BAR; PG8_SCHED;
;             PG8_LDB(B1, 0, 1); PG8_STAGE(PG8_SB(0, 0), b2, voffB);
;             PG8_BAR; PG8_WAIT_L(0); PG8_MMA(0, 1, At, B1); PG8_BAR;
;             PG8_LDA(At, 0, 1); PG8_STAGE(PG8_SA(0, 0), a2, voffA);
;             PG8_BAR; PG8_WAIT_L(0); PG8_MMA(1, 0, At, B0); PG8_BAR; PG8_SCHED;
.LBB0_871:
	v_add_u32_e32 v162, s47, v148
	s_add_u32 s28, s12, s26
	ds_read_b128 v[150:153], v162
	ds_read_b128 v[154:157], v162 offset:1024
	ds_read_b128 v[158:161], v162 offset:2048
	ds_read_b128 v[162:165], v162 offset:3072
	s_addc_u32 s29, s13, s27
	s_add_u32 s28, s28, 0x100
	s_addc_u32 s29, s29, 0
	s_add_u32 s53, s23, s26
	s_addc_u32 s54, s49, s27
	s_cmpk_eq_i32 s26, 0x700
	s_cselect_b32 s31, s19, s29
	s_cselect_b32 s30, s50, s28
	s_cselect_b32 s29, s17, s54
	s_cselect_b32 s28, s51, s53
	v_lshl_add_u64 v[202:203], v[144:145], 0, s[26:27]
	s_add_i32 m0, s40, 0xc000
	ds_read_b128 v[166:169], v149
	ds_read_b128 v[170:173], v149 offset:1024
	ds_read_b128 v[174:177], v149 offset:2048
	ds_read_b128 v[178:181], v149 offset:3072
	ds_read_b128 v[182:185], v149 offset:4096
	ds_read_b128 v[186:189], v149 offset:5120
	ds_read_b128 v[190:193], v149 offset:6144
	ds_read_b128 v[198:201], v149 offset:7168
	global_load_lds_dwordx4 v[202:203], off
	v_lshl_add_u64 v[202:203], v[146:147], 0, s[26:27]
	s_add_i32 m0, s40, 0xe000
	s_nop 0
	global_load_lds_dwordx4 v[202:203], off
	s_waitcnt lgkmcnt(8)
	s_barrier
	s_waitcnt lgkmcnt(0)
	s_setprio 1
	s_waitcnt lgkmcnt(0)
	v_mfma_f32_16x16x32_bf16 v[124:127], v[150:153], v[166:169], v[124:127]
	v_mfma_f32_16x16x32_bf16 v[120:123], v[158:161], v[166:169], v[120:123]
	v_mfma_f32_16x16x32_bf16 v[100:103], v[150:153], v[174:177], v[100:103]
	v_mfma_f32_16x16x32_bf16 v[96:99], v[158:161], v[174:177], v[96:99]
	v_mfma_f32_16x16x32_bf16 v[116:119], v[150:153], v[182:185], v[116:119]
	v_mfma_f32_16x16x32_bf16 v[112:115], v[158:161], v[182:185], v[112:115]
	v_mfma_f32_16x16x32_bf16 v[76:79], v[150:153], v[190:193], v[76:79]
	v_mfma_f32_16x16x32_bf16 v[72:75], v[158:161], v[190:193], v[72:75]
	v_mfma_f32_16x16x32_bf16 v[124:127], v[154:157], v[170:173], v[124:127]
	v_mfma_f32_16x16x32_bf16 v[120:123], v[162:165], v[170:173], v[120:123]
	v_mfma_f32_16x16x32_bf16 v[100:103], v[154:157], v[178:181], v[100:103]
	v_mfma_f32_16x16x32_bf16 v[96:99], v[162:165], v[178:181], v[96:99]
	v_mfma_f32_16x16x32_bf16 v[116:119], v[154:157], v[186:189], v[116:119]
	v_mfma_f32_16x16x32_bf16 v[112:115], v[162:165], v[186:189], v[112:115]
	v_mfma_f32_16x16x32_bf16 v[76:79], v[154:157], v[198:201], v[76:79]
	v_mfma_f32_16x16x32_bf16 v[72:75], v[162:165], v[198:201], v[72:75]
	s_setprio 0
	s_barrier
	v_add_u32_e32 v210, s48, v148
	s_add_i32 s53, s47, s39
	ds_read_b128 v[202:205], v210
	ds_read_b128 v[206:209], v210 offset:1024
	ds_read_b128 v[214:217], v210 offset:2048
	ds_read_b128 v[218:221], v210 offset:3072
	v_lshl_add_u64 v[210:211], s[28:29], 0, v[130:131]
	s_mov_b32 m0, s53
	v_lshl_add_u64 v[222:223], s[28:29], 0, v[134:135]
	global_load_lds_dwordx4 v[210:211], off
	s_add_i32 m0, s53, 0x2000
	s_nop 0
	global_load_lds_dwordx4 v[222:223], off
	s_barrier
	s_waitcnt lgkmcnt(0)
	s_setprio 1
	s_waitcnt lgkmcnt(0)
	v_mfma_f32_16x16x32_bf16 v[108:111], v[202:205], v[166:169], v[108:111]
	v_mfma_f32_16x16x32_bf16 v[104:107], v[214:217], v[166:169], v[104:107]
	v_mfma_f32_16x16x32_bf16 v[88:91], v[202:205], v[174:177], v[88:91]
	v_mfma_f32_16x16x32_bf16 v[84:87], v[214:217], v[174:177], v[84:87]
	v_mfma_f32_16x16x32_bf16 v[92:95], v[202:205], v[182:185], v[92:95]
	v_mfma_f32_16x16x32_bf16 v[80:83], v[214:217], v[182:185], v[80:83]
	v_mfma_f32_16x16x32_bf16 v[68:71], v[202:205], v[190:193], v[68:71]
	v_mfma_f32_16x16x32_bf16 v[64:67], v[214:217], v[190:193], v[64:67]
	v_mfma_f32_16x16x32_bf16 v[108:111], v[206:209], v[170:173], v[108:111]
	v_mfma_f32_16x16x32_bf16 v[104:107], v[218:221], v[170:173], v[104:107]
	v_mfma_f32_16x16x32_bf16 v[88:91], v[206:209], v[178:181], v[88:91]
	v_mfma_f32_16x16x32_bf16 v[84:87], v[218:221], v[178:181], v[84:87]
	v_mfma_f32_16x16x32_bf16 v[92:95], v[206:209], v[186:189], v[92:95]
	v_mfma_f32_16x16x32_bf16 v[80:83], v[218:221], v[186:189], v[80:83]
	v_mfma_f32_16x16x32_bf16 v[68:71], v[206:209], v[198:201], v[68:71]
	v_mfma_f32_16x16x32_bf16 v[64:67], v[218:221], v[198:201], v[64:67]
	s_setprio 0
	s_mov_b32 m0, s40
	v_lshl_add_u64 v[224:225], s[30:31], 0, v[128:129]
	s_barrier
	ds_read_b128 v[166:169], v149 offset:16384
	ds_read_b128 v[170:173], v149 offset:17408
	ds_read_b128 v[174:177], v149 offset:18432
	ds_read_b128 v[178:181], v149 offset:19456
	ds_read_b128 v[182:185], v149 offset:20480
	ds_read_b128 v[186:189], v149 offset:21504
	ds_read_b128 v[190:193], v149 offset:22528
	ds_read_b128 v[198:201], v149 offset:23552
	global_load_lds_dwordx4 v[224:225], off
	v_lshl_add_u64 v[226:227], s[30:31], 0, v[132:133]
	s_mov_b32 m0, s41
	s_nop 0
	global_load_lds_dwordx4 v[226:227], off
	s_barrier
	s_waitcnt lgkmcnt(0)
	s_setprio 1
	s_waitcnt lgkmcnt(0)
	v_mfma_f32_16x16x32_bf16 v[60:63], v[150:153], v[166:169], v[60:63]
	v_mfma_f32_16x16x32_bf16 v[56:59], v[158:161], v[166:169], v[56:59]
	v_mfma_f32_16x16x32_bf16 v[52:55], v[150:153], v[174:177], v[52:55]
	v_mfma_f32_16x16x32_bf16 v[40:43], v[158:161], v[174:177], v[40:43]
	v_mfma_f32_16x16x32_bf16 v[32:35], v[150:153], v[182:185], v[32:35]
	v_mfma_f32_16x16x32_bf16 v[28:31], v[158:161], v[182:185], v[28:31]
	v_mfma_f32_16x16x32_bf16 v[20:23], v[150:153], v[190:193], v[20:23]
	v_mfma_f32_16x16x32_bf16 v[8:11], v[158:161], v[190:193], v[8:11]
	v_mfma_f32_16x16x32_bf16 v[60:63], v[154:157], v[170:173], v[60:63]
	v_mfma_f32_16x16x32_bf16 v[56:59], v[162:165], v[170:173], v[56:59]
	v_mfma_f32_16x16x32_bf16 v[52:55], v[154:157], v[178:181], v[52:55]
	v_mfma_f32_16x16x32_bf16 v[40:43], v[162:165], v[178:181], v[40:43]
	v_mfma_f32_16x16x32_bf16 v[32:35], v[154:157], v[186:189], v[32:35]
	v_mfma_f32_16x16x32_bf16 v[28:31], v[162:165], v[186:189], v[28:31]
	v_mfma_f32_16x16x32_bf16 v[20:23], v[154:157], v[198:201], v[20:23]
	v_mfma_f32_16x16x32_bf16 v[8:11], v[162:165], v[198:201], v[8:11]
	s_setprio 0
	s_barrier
; #define PG8_STAGE(bufoff, gbase, voff) do { _Pragma("unroll") for (int _i = 0; _i < 2; ++_i) \
;         __builtin_amdgcn_global_load_lds((const unsigned*)((const char*)(gbase) + (voff)[_i]), (LAS unsigned*)(lds + (bufoff) + ldsw + _i * 8192), 16, 0, 0); } while (0)
; #define PG8_LDA(dst, b, h) do { _Pragma("unroll") for (int m = 0; m < 4; ++m) _Pragma("unroll") for (int k = 0; k < 2; ++k) dst[m][k] = *(const LAS bf16x8*)(lds + PG8_SA(b, h) + aoff + m * 2048 + k * 1024); } while (0)
; #define PG8_LDB(dst, b, h) do { _Pragma("unroll") for (int n = 0; n < 2; ++n) _Pragma("unroll") for (int k = 0; k < 2; ++k) dst[n][k] = *(const LAS bf16x8*)(lds + PG8_SB(b, h) + boff + n * 2048 + k * 1024); } while (0)
; #define PG8_MMA(ai, bj, At, Bt) do { __builtin_amdgcn_s_setprio(1); _Pragma("unroll") for (int m = 0; m < 4; ++m) _Pragma("unroll") for (int n = 0; n < 2; ++n) _Pragma("unroll") for (int k = 0; k < 2; ++k) \
;         acc[ai][bj][m][n] = __builtin_amdgcn_mfma_f32_16x16x32_bf16(Bt[n][k], At[m][k], acc[ai][bj][m][n], 0, 0, 0); __builtin_amdgcn_s_setprio(0); } while (0)
; #define PG8_WAIT_V(n) asm volatile("s_waitcnt vmcnt(" #n ")" ::: "memory")
; #define PG8_WAIT_L(n) asm volatile("s_waitcnt lgkmcnt(" #n ")" ::: "memory")
; #define PG8_BAR __builtin_amdgcn_s_barrier()
; #define PG8_SCHED __builtin_amdgcn_sched_barrier(0)
; #define PG8_LDA(dst, b, h) do { _Pragma("unroll") for (int m = 0; m < 4; ++m) _Pragma("unroll") for (int k = 0; k < 2; ++k) dst[m][k] = *(const LAS bf16x8*)(lds + PG8_SA(b, h) + aoff + m * 2048 + k * 1024); } while (0)
; #define PG8_BAR __builtin_amdgcn_s_barrier()
; template <class Epi, bool AFTER = false>
; __device__ __forceinline__ void gemm_phase(LAS unsigned char* lds, const Gemm g, const StaticOrder& S, const Epi& E) {
;     ...
;             PG8_STAGE(PG8_SB(0, 1), b2 + hstep, voffB);
;             PG8_WAIT_V(6); PG8_BAR; PG8_MMA(1, 1, At, B1); PG8_BAR;
;             PG8_LDB(B0, 1, 0); PG8_SCHED; PG8_LDA(At, 1, 0); PG8_STAGE(PG8_SA(0, 1), a2 + hstep, voffA);
;             PG8_WAIT_L(8); PG8_BAR; PG8_WAIT_L(0); PG8_MMA(0, 0, At, B0); PG8_BAR; PG8_SCHED;
;             PG8_LDB(B1, 1, 1); PG8_STAGE(PG8_SB(1, 0), b3, voffB);
;             PG8_BAR; PG8_WAIT_L(0); PG8_MMA(0, 1, At, B1); PG8_BAR;
;             PG8_LDA(At, 1, 1); PG8_STAGE(PG8_SA(1, 0), a3, voffA);
;             PG8_BAR; PG8_WAIT_L(0); PG8_MMA(1, 0, At, B0); PG8_BAR; PG8_SCHED;
	s_add_u32 s54, s28, 0x40000
	s_addc_u32 s55, s29, 0
	s_add_i32 s53, s48, s39
	v_lshl_add_u64 v[150:151], s[54:55], 0, v[130:131]
	s_mov_b32 m0, s53
	s_nop 0
	global_load_lds_dwordx4 v[150:151], off
	v_lshl_add_u64 v[150:151], s[54:55], 0, v[134:135]
	s_add_i32 m0, s53, 0x2000
	s_nop 0
	global_load_lds_dwordx4 v[150:151], off
	s_waitcnt vmcnt(6)
	s_barrier
	s_setprio 1
	v_mfma_f32_16x16x32_bf16 v[48:51], v[202:205], v[166:169], v[48:51]
	v_mfma_f32_16x16x32_bf16 v[44:47], v[214:217], v[166:169], v[44:47]
	v_mfma_f32_16x16x32_bf16 v[36:39], v[202:205], v[174:177], v[36:39]
	v_mfma_f32_16x16x32_bf16 v[24:27], v[214:217], v[174:177], v[24:27]
	v_mfma_f32_16x16x32_bf16 v[16:19], v[202:205], v[182:185], v[16:19]
	v_mfma_f32_16x16x32_bf16 v[12:15], v[214:217], v[182:185], v[12:15]
	v_mfma_f32_16x16x32_bf16 v[4:7], v[202:205], v[190:193], v[4:7]
	v_mfma_f32_16x16x32_bf16 v[0:3], v[214:217], v[190:193], v[0:3]
	v_mfma_f32_16x16x32_bf16 v[48:51], v[206:209], v[170:173], v[48:51]
	v_mfma_f32_16x16x32_bf16 v[44:47], v[218:221], v[170:173], v[44:47]
	v_mfma_f32_16x16x32_bf16 v[36:39], v[206:209], v[178:181], v[36:39]
	v_mfma_f32_16x16x32_bf16 v[24:27], v[218:221], v[178:181], v[24:27]
	v_mfma_f32_16x16x32_bf16 v[16:19], v[206:209], v[186:189], v[16:19]
	v_mfma_f32_16x16x32_bf16 v[12:15], v[218:221], v[186:189], v[12:15]
	v_mfma_f32_16x16x32_bf16 v[4:7], v[206:209], v[198:201], v[4:7]
	v_mfma_f32_16x16x32_bf16 v[0:3], v[218:221], v[198:201], v[0:3]
	s_setprio 0
	s_add_i32 s53, 0, 0x18000
	v_add_u32_e32 v162, s53, v148
	s_barrier
	ds_read_b128 v[150:153], v162
	ds_read_b128 v[154:157], v162 offset:1024
	ds_read_b128 v[158:161], v162 offset:2048
	ds_read_b128 v[162:165], v162 offset:3072
	s_add_u32 s30, s30, 0x40000
	s_addc_u32 s31, s31, 0
	s_mov_b32 m0, s42
	v_lshl_add_u64 v[202:203], s[30:31], 0, v[128:129]
	ds_read_b128 v[166:169], v149 offset:32768
	ds_read_b128 v[170:173], v149 offset:33792
	ds_read_b128 v[174:177], v149 offset:34816
	ds_read_b128 v[178:181], v149 offset:35840
	ds_read_b128 v[182:185], v149 offset:36864
	ds_read_b128 v[186:189], v149 offset:37888
	ds_read_b128 v[190:193], v149 offset:38912
	ds_read_b128 v[198:201], v149 offset:39936
	global_load_lds_dwordx4 v[202:203], off
	v_lshl_add_u64 v[202:203], s[30:31], 0, v[132:133]
	s_mov_b32 m0, s43
	s_nop 0
	global_load_lds_dwordx4 v[202:203], off
	s_waitcnt lgkmcnt(8)
	s_barrier
	s_waitcnt lgkmcnt(0)
	s_setprio 1
	s_waitcnt lgkmcnt(0)
	v_mfma_f32_16x16x32_bf16 v[124:127], v[150:153], v[166:169], v[124:127]
	v_mfma_f32_16x16x32_bf16 v[120:123], v[158:161], v[166:169], v[120:123]
	v_mfma_f32_16x16x32_bf16 v[100:103], v[150:153], v[174:177], v[100:103]
	v_mfma_f32_16x16x32_bf16 v[96:99], v[158:161], v[174:177], v[96:99]
	v_mfma_f32_16x16x32_bf16 v[116:119], v[150:153], v[182:185], v[116:119]
	v_mfma_f32_16x16x32_bf16 v[112:115], v[158:161], v[182:185], v[112:115]
	v_mfma_f32_16x16x32_bf16 v[76:79], v[150:153], v[190:193], v[76:79]
	v_mfma_f32_16x16x32_bf16 v[72:75], v[158:161], v[190:193], v[72:75]
	v_mfma_f32_16x16x32_bf16 v[124:127], v[154:157], v[170:173], v[124:127]
	v_mfma_f32_16x16x32_bf16 v[120:123], v[162:165], v[170:173], v[120:123]
	v_mfma_f32_16x16x32_bf16 v[100:103], v[154:157], v[178:181], v[100:103]
	v_mfma_f32_16x16x32_bf16 v[96:99], v[162:165], v[178:181], v[96:99]
	v_mfma_f32_16x16x32_bf16 v[116:119], v[154:157], v[186:189], v[116:119]
	v_mfma_f32_16x16x32_bf16 v[112:115], v[162:165], v[186:189], v[112:115]
	v_mfma_f32_16x16x32_bf16 v[76:79], v[154:157], v[198:201], v[76:79]
	v_mfma_f32_16x16x32_bf16 v[72:75], v[162:165], v[198:201], v[72:75]
	s_setprio 0
	s_barrier
	s_add_i32 s30, 0, 0x1c000
	s_add_i32 s31, s53, s39
	v_add_u32_e32 v218, s30, v148
	v_lshl_add_u64 v[210:211], v[210:211], 0, s[14:15]
	s_mov_b32 m0, s31
	ds_read_b128 v[202:205], v218
	ds_read_b128 v[206:209], v218 offset:1024
	ds_read_b128 v[214:217], v218 offset:2048
	ds_read_b128 v[218:221], v218 offset:3072
	global_load_lds_dwordx4 v[210:211], off
	v_lshl_add_u64 v[210:211], v[222:223], 0, s[14:15]
	s_add_i32 m0, s31, 0x2000
	s_nop 0
	global_load_lds_dwordx4 v[210:211], off
	s_barrier
; #define PG8_STAGE(bufoff, gbase, voff) do { _Pragma("unroll") for (int _i = 0; _i < 2; ++_i) \
;         __builtin_amdgcn_global_load_lds((const unsigned*)((const char*)(gbase) + (voff)[_i]), (LAS unsigned*)(lds + (bufoff) + ldsw + _i * 8192), 16, 0, 0); } while (0)
; #define PG8_MMA(ai, bj, At, Bt) do { __builtin_amdgcn_s_setprio(1); _Pragma("unroll") for (int m = 0; m < 4; ++m) _Pragma("unroll") for (int n = 0; n < 2; ++n) _Pragma("unroll") for (int k = 0; k < 2; ++k) \
;         acc[ai][bj][m][n] = __builtin_amdgcn_mfma_f32_16x16x32_bf16(Bt[n][k], At[m][k], acc[ai][bj][m][n], 0, 0, 0); __builtin_amdgcn_s_setprio(0); } while (0)
; #define PG8_WAIT_V(n) asm volatile("s_waitcnt vmcnt(" #n ")" ::: "memory")
; #define PG8_WAIT_L(n) asm volatile("s_waitcnt lgkmcnt(" #n ")" ::: "memory")
; #define PG8_BAR __builtin_amdgcn_s_barrier()
; #define PG8_SCHED __builtin_amdgcn_sched_barrier(0)
; #define PG8_MMA(ai, bj, At, Bt) do { __builtin_amdgcn_s_setprio(1); _Pragma("unroll") for (int m = 0; m < 4; ++m) _Pragma("unroll") for (int n = 0; n < 2; ++n) _Pragma("unroll") for (int k = 0; k < 2; ++k) \
;         acc[ai][bj][m][n] = __builtin_amdgcn_mfma_f32_16x16x32_bf16(Bt[n][k], At[m][k], acc[ai][bj][m][n], 0, 0, 0); __builtin_amdgcn_s_setprio(0); } while (0)
; #define PG8_WAIT_V(n) asm volatile("s_waitcnt vmcnt(" #n ")" ::: "memory")
; #define PG8_WAIT_L(n) asm volatile("s_waitcnt lgkmcnt(" #n ")" ::: "memory")
; #define PG8_BAR __builtin_amdgcn_s_barrier()
; #define PG8_SCHED __builtin_amdgcn_sched_barrier(0)
; template <class Epi, bool AFTER = false>
; __device__ __forceinline__ void gemm_phase(LAS unsigned char* lds, const Gemm g, const StaticOrder& S, const Epi& E) {
;     ...
;             PG8_BAR; PG8_WAIT_L(0); PG8_MMA(1, 0, At, B0); PG8_BAR; PG8_SCHED;
;             PG8_STAGE(PG8_SB(1, 1), b3 + hstep, voffB);
;             PG8_WAIT_V(6); PG8_BAR; PG8_MMA(1, 1, At, B1); PG8_BAR;
	s_waitcnt lgkmcnt(0)
	s_setprio 1
	s_waitcnt lgkmcnt(0)
	v_mfma_f32_16x16x32_bf16 v[108:111], v[202:205], v[166:169], v[108:111]
	v_mfma_f32_16x16x32_bf16 v[104:107], v[214:217], v[166:169], v[104:107]
	v_mfma_f32_16x16x32_bf16 v[88:91], v[202:205], v[174:177], v[88:91]
	v_mfma_f32_16x16x32_bf16 v[84:87], v[214:217], v[174:177], v[84:87]
	v_mfma_f32_16x16x32_bf16 v[92:95], v[202:205], v[182:185], v[92:95]
	v_mfma_f32_16x16x32_bf16 v[80:83], v[214:217], v[182:185], v[80:83]
	v_mfma_f32_16x16x32_bf16 v[68:71], v[202:205], v[190:193], v[68:71]
	v_mfma_f32_16x16x32_bf16 v[64:67], v[214:217], v[190:193], v[64:67]
	v_mfma_f32_16x16x32_bf16 v[108:111], v[206:209], v[170:173], v[108:111]
	v_mfma_f32_16x16x32_bf16 v[104:107], v[218:221], v[170:173], v[104:107]
	v_mfma_f32_16x16x32_bf16 v[88:91], v[206:209], v[178:181], v[88:91]
	v_mfma_f32_16x16x32_bf16 v[84:87], v[218:221], v[178:181], v[84:87]
	v_mfma_f32_16x16x32_bf16 v[92:95], v[206:209], v[186:189], v[92:95]
	v_mfma_f32_16x16x32_bf16 v[80:83], v[218:221], v[186:189], v[80:83]
	v_mfma_f32_16x16x32_bf16 v[68:71], v[206:209], v[198:201], v[68:71]
	v_mfma_f32_16x16x32_bf16 v[64:67], v[218:221], v[198:201], v[64:67]
	s_setprio 0
	s_mov_b32 m0, s44
	v_lshl_add_u64 v[210:211], v[224:225], 0, s[14:15]
	s_barrier
	ds_read_b128 v[166:169], v149 offset:49152
	ds_read_b128 v[170:173], v149 offset:50176
	ds_read_b128 v[174:177], v149 offset:51200
	ds_read_b128 v[178:181], v149 offset:52224
	ds_read_b128 v[182:185], v149 offset:53248
	ds_read_b128 v[186:189], v149 offset:54272
	ds_read_b128 v[190:193], v149 offset:55296
	ds_read_b128 v[198:201], v149 offset:56320
	global_load_lds_dwordx4 v[210:211], off
	v_lshl_add_u64 v[210:211], v[226:227], 0, s[14:15]
	s_mov_b32 m0, s45
	s_nop 0
	global_load_lds_dwordx4 v[210:211], off
	s_barrier
	s_waitcnt lgkmcnt(0)
	s_setprio 1
	s_waitcnt lgkmcnt(0)
	v_mfma_f32_16x16x32_bf16 v[60:63], v[150:153], v[166:169], v[60:63]
	v_mfma_f32_16x16x32_bf16 v[56:59], v[158:161], v[166:169], v[56:59]
	v_mfma_f32_16x16x32_bf16 v[52:55], v[150:153], v[174:177], v[52:55]
	v_mfma_f32_16x16x32_bf16 v[40:43], v[158:161], v[174:177], v[40:43]
	v_mfma_f32_16x16x32_bf16 v[32:35], v[150:153], v[182:185], v[32:35]
	v_mfma_f32_16x16x32_bf16 v[28:31], v[158:161], v[182:185], v[28:31]
	v_mfma_f32_16x16x32_bf16 v[20:23], v[150:153], v[190:193], v[20:23]
	v_mfma_f32_16x16x32_bf16 v[8:11], v[158:161], v[190:193], v[8:11]
	v_mfma_f32_16x16x32_bf16 v[60:63], v[154:157], v[170:173], v[60:63]
	v_mfma_f32_16x16x32_bf16 v[56:59], v[162:165], v[170:173], v[56:59]
	v_mfma_f32_16x16x32_bf16 v[52:55], v[154:157], v[178:181], v[52:55]
	v_mfma_f32_16x16x32_bf16 v[40:43], v[162:165], v[178:181], v[40:43]
	v_mfma_f32_16x16x32_bf16 v[32:35], v[154:157], v[186:189], v[32:35]
	v_mfma_f32_16x16x32_bf16 v[28:31], v[162:165], v[186:189], v[28:31]
	v_mfma_f32_16x16x32_bf16 v[20:23], v[154:157], v[198:201], v[20:23]
	v_mfma_f32_16x16x32_bf16 v[8:11], v[162:165], v[198:201], v[8:11]
	s_setprio 0
	s_barrier
	s_add_u32 s28, s28, 0x40080
	s_addc_u32 s29, s29, 0
	s_add_i32 s30, s30, s39
	v_lshl_add_u64 v[150:151], s[28:29], 0, v[130:131]
	s_mov_b32 m0, s30
	s_nop 0
	global_load_lds_dwordx4 v[150:151], off
	v_lshl_add_u64 v[150:151], s[28:29], 0, v[134:135]
	s_add_i32 m0, s30, 0x2000
	s_nop 0
	global_load_lds_dwordx4 v[150:151], off
	s_waitcnt vmcnt(6)
	s_barrier
	s_setprio 1
	v_mfma_f32_16x16x32_bf16 v[48:51], v[202:205], v[166:169], v[48:51]
	v_mfma_f32_16x16x32_bf16 v[44:47], v[214:217], v[166:169], v[44:47]
	v_mfma_f32_16x16x32_bf16 v[36:39], v[202:205], v[174:177], v[36:39]
	v_mfma_f32_16x16x32_bf16 v[24:27], v[214:217], v[174:177], v[24:27]
	v_mfma_f32_16x16x32_bf16 v[16:19], v[202:205], v[182:185], v[16:19]
	v_mfma_f32_16x16x32_bf16 v[12:15], v[214:217], v[182:185], v[12:15]
	v_mfma_f32_16x16x32_bf16 v[4:7], v[202:205], v[190:193], v[4:7]
	v_mfma_f32_16x16x32_bf16 v[0:3], v[214:217], v[190:193], v[0:3]
	v_mfma_f32_16x16x32_bf16 v[48:51], v[206:209], v[170:173], v[48:51]
	v_mfma_f32_16x16x32_bf16 v[44:47], v[218:221], v[170:173], v[44:47]
	v_mfma_f32_16x16x32_bf16 v[36:39], v[206:209], v[178:181], v[36:39]
	v_mfma_f32_16x16x32_bf16 v[24:27], v[218:221], v[178:181], v[24:27]
	v_mfma_f32_16x16x32_bf16 v[16:19], v[206:209], v[186:189], v[16:19]
	v_mfma_f32_16x16x32_bf16 v[12:15], v[218:221], v[186:189], v[12:15]
	v_mfma_f32_16x16x32_bf16 v[4:7], v[206:209], v[198:201], v[4:7]
	v_mfma_f32_16x16x32_bf16 v[0:3], v[218:221], v[198:201], v[0:3]
	s_setprio 0
	s_add_i32 s52, s52, 2
	s_add_u32 s26, s26, 0x100
	s_addc_u32 s27, s27, 0
	s_cmp_gt_u32 s52, 13
	s_barrier
	s_cbranch_scc0 .LBB0_871
	s_cmp_eq_u32 s98, 1
	s_cbranch_scc0 .Lw7_done
	s_mov_b32 s98, 0
	v_readfirstlane_b32 s96, v212
	s_nop 3
	s_cmp_lg_u32 s96, 0
	s_cbranch_scc1 .Lw7_bar
	v_readlane_b32 s96, v254, 3
	s_nop 3
	s_lshl_b32 s96, s96, 8
	v_mov_b32_e32 v250, 0xffc3500
	v_mov_b32_e32 v251, 0xffc2400
	v_add_u32_e32 v251, s96, v251
	s_mov_b32 s96, 0
.Lw7_spin:
	global_load_dword v252, v250, s[88:89] sc1
	global_load_dword v253, v251, s[88:89] sc1
	s_waitcnt vmcnt(0)
	v_min_u32_e32 v252, v252, v253
	s_nop 1
	v_readfirstlane_b32 s97, v252
	s_nop 3
	s_cmp_ge_u32 s97, 8
	s_cbranch_scc1 .Lw7_bar
	s_sleep 1
	s_add_i32 s96, s96, 1
	s_cmp_lt_u32 s96, 0x40000
	s_cbranch_scc1 .Lw7_spin

; template <class Epi, bool AFTER = false>
; __device__ __forceinline__ void gemm_phase(LAS unsigned char* lds, const Gemm g, const StaticOrder& S, const Epi& E) {
;     ...
;         if constexpr (!AFTER) E(acc, cur, wr, wc, fr, fq);
;         if (!has_next) break;
; #pragma unroll
;         for (int a = 0; a < 2; ++a)
; #pragma unroll
;             for (int b = 0; b < 2; ++b)
; #pragma unroll
;                 for (int m = 0; m < 4; ++m)
; #pragma unroll
;                     for (int n = 0; n < 2; ++n) acc[a][b][m][n] = (f32x4){0.f, 0.f, 0.f, 0.f};
;         cur = nxt; cA = nA; cB = nB; ++ui;
.Lw7_done:
	s_add_u32 s26, s23, 0xffffff00
	s_addc_u32 s27, s49, -1
	s_andn2_b64 vcc, exec, s[4:5]
	s_cbranch_vccnz .LBB0_862
	v_mov_b32_e32 v0, 0
	s_mov_b32 s10, s16
	s_mov_b32 s8, s18
	s_mov_b64 s[12:13], s[24:25]
	s_mov_b32 s46, s22
	v_mov_b32_e32 v1, v0
	v_mov_b32_e32 v2, v0
	v_mov_b32_e32 v3, v0
	v_mov_b32_e32 v4, v0
	v_mov_b32_e32 v5, v0
	v_mov_b32_e32 v6, v0
	v_mov_b32_e32 v7, v0
	v_mov_b32_e32 v12, v0
	v_mov_b32_e32 v13, v0
	v_mov_b32_e32 v14, v0
	v_mov_b32_e32 v15, v0
	v_mov_b32_e32 v16, v0
	v_mov_b32_e32 v17, v0
	v_mov_b32_e32 v18, v0
	v_mov_b32_e32 v19, v0
	v_mov_b32_e32 v24, v0
	v_mov_b32_e32 v25, v0
	v_mov_b32_e32 v26, v0
	v_mov_b32_e32 v27, v0
	v_mov_b32_e32 v36, v0
	v_mov_b32_e32 v37, v0
	v_mov_b32_e32 v38, v0
	v_mov_b32_e32 v39, v0
	v_mov_b32_e32 v44, v0
	v_mov_b32_e32 v45, v0
	v_mov_b32_e32 v46, v0
	v_mov_b32_e32 v47, v0
	v_mov_b32_e32 v48, v0
	v_mov_b32_e32 v49, v0
	v_mov_b32_e32 v50, v0
	v_mov_b32_e32 v51, v0
	v_mov_b32_e32 v8, v0
	v_mov_b32_e32 v9, v0
	v_mov_b32_e32 v10, v0
	v_mov_b32_e32 v11, v0
	v_mov_b32_e32 v20, v0
	v_mov_b32_e32 v21, v0
	v_mov_b32_e32 v22, v0
	v_mov_b32_e32 v23, v0
	v_mov_b32_e32 v28, v0
	v_mov_b32_e32 v29, v0
	v_mov_b32_e32 v30, v0
	v_mov_b32_e32 v31, v0
	v_mov_b32_e32 v32, v0
	v_mov_b32_e32 v33, v0
	v_mov_b32_e32 v34, v0
	v_mov_b32_e32 v35, v0
	v_mov_b32_e32 v40, v0
	v_mov_b32_e32 v41, v0
	v_mov_b32_e32 v42, v0
	v_mov_b32_e32 v43, v0
	v_mov_b32_e32 v52, v0
	v_mov_b32_e32 v53, v0
	v_mov_b32_e32 v54, v0
	v_mov_b32_e32 v55, v0
	v_mov_b32_e32 v56, v0
	v_mov_b32_e32 v57, v0
	v_mov_b32_e32 v58, v0
	v_mov_b32_e32 v59, v0
	v_mov_b32_e32 v60, v0
	v_mov_b32_e32 v61, v0
	v_mov_b32_e32 v62, v0
	v_mov_b32_e32 v63, v0
	v_mov_b32_e32 v64, v0
	v_mov_b32_e32 v65, v0
	v_mov_b32_e32 v66, v0
	v_mov_b32_e32 v67, v0
	v_mov_b32_e32 v68, v0
	v_mov_b32_e32 v69, v0
	v_mov_b32_e32 v70, v0
	v_mov_b32_e32 v71, v0
	v_mov_b32_e32 v80, v0
	v_mov_b32_e32 v81, v0
	v_mov_b32_e32 v82, v0
	v_mov_b32_e32 v83, v0
	v_mov_b32_e32 v92, v0
	v_mov_b32_e32 v93, v0
	v_mov_b32_e32 v94, v0
	v_mov_b32_e32 v95, v0
	v_mov_b32_e32 v84, v0
	v_mov_b32_e32 v85, v0
	v_mov_b32_e32 v86, v0
	v_mov_b32_e32 v87, v0
	v_mov_b32_e32 v88, v0
	v_mov_b32_e32 v89, v0
	v_mov_b32_e32 v90, v0
	v_mov_b32_e32 v91, v0
	v_mov_b32_e32 v104, v0
	v_mov_b32_e32 v105, v0
	v_mov_b32_e32 v106, v0
	v_mov_b32_e32 v107, v0
	v_mov_b32_e32 v108, v0
	v_mov_b32_e32 v109, v0
	v_mov_b32_e32 v110, v0
	v_mov_b32_e32 v111, v0
	v_mov_b32_e32 v72, v0
	v_mov_b32_e32 v73, v0
	v_mov_b32_e32 v74, v0
	v_mov_b32_e32 v75, v0
	v_mov_b32_e32 v76, v0
	v_mov_b32_e32 v77, v0
	v_mov_b32_e32 v78, v0
	v_mov_b32_e32 v79, v0
	v_mov_b32_e32 v112, v0
	v_mov_b32_e32 v113, v0
	v_mov_b32_e32 v114, v0
	v_mov_b32_e32 v115, v0
	v_mov_b32_e32 v116, v0
	v_mov_b32_e32 v117, v0
	v_mov_b32_e32 v118, v0
	v_mov_b32_e32 v119, v0
	v_mov_b32_e32 v96, v0
	v_mov_b32_e32 v97, v0
	v_mov_b32_e32 v98, v0
	v_mov_b32_e32 v99, v0
	v_mov_b32_e32 v100, v0
	v_mov_b32_e32 v101, v0
	v_mov_b32_e32 v102, v0
	v_mov_b32_e32 v103, v0
	v_mov_b32_e32 v120, v0
	v_mov_b32_e32 v121, v0
	v_mov_b32_e32 v122, v0
	v_mov_b32_e32 v123, v0
	v_mov_b32_e32 v124, v0
	v_mov_b32_e32 v125, v0
	v_mov_b32_e32 v126, v0
	v_mov_b32_e32 v127, v0
	s_andn2_b64 vcc, exec, s[2:3]
	s_cbranch_vccnz .LBB0_863
